# even in-projection epilogue: rs loads hoisted, per-iteration drains removed
# speedup vs baseline: 1.0003x; 1.0003x over previous
.LBB0_881:
	s_min_i32 s0, s28, 64
	s_lshr_b32 s0, s0, 4
	s_mulk_i32 s0, 0x1600
	s_ashr_i32 s1, s0, 31
	s_lshl_b64 s[0:1], s[0:1], 2
	s_add_u32 s5, s47, s0
	s_addc_u32 s21, s48, s1
	s_lshl_b32 s30, s4, 8
	s_ashr_i32 s31, s30, 31
	s_lshl_b64 s[0:1], s[30:31], 2
	s_add_u32 s0, s5, s0
	s_addc_u32 s1, s21, s1
	s_add_u32 s0, s0, s53
	s_addc_u32 s1, s1, 0
	s_cmp_lt_i32 s28, 64
	global_load_dwordx4 v[62:65], v188, s[0:1]
	global_load_dwordx4 v[58:61], v188, s[0:1] offset:64
	global_load_dwordx4 v[54:57], v188, s[0:1] offset:512
	global_load_dwordx4 v[50:53], v188, s[0:1] offset:576
	s_cselect_b64 s[0:1], -1, 0
	s_lshl_b32 s21, s28, 8
	s_add_i32 s21, s21, s49
	v_or_b32_e32 v164, s21, v1
	v_ashrrev_i32_e32 v165, 31, v164
	v_lshl_add_u64 v[166:167], v[164:165], 2, s[12:13]
	global_load_dword v166, v[166:167], off
	s_add_i32 s84, s21, 0x80
	v_or_b32_e32 v194, s21, v184
	v_ashrrev_i32_e32 v195, 31, v194
	v_lshl_add_u64 v[194:195], v[194:195], 2, s[12:13]
	global_load_dword v210, v[194:195], off
	v_or_b32_e32 v196, s21, v185
	v_ashrrev_i32_e32 v197, 31, v196
	v_lshl_add_u64 v[196:197], v[196:197], 2, s[12:13]
	global_load_dword v211, v[196:197], off
	v_or_b32_e32 v198, s21, v186
	v_ashrrev_i32_e32 v199, 31, v198
	v_lshl_add_u64 v[198:199], v[198:199], 2, s[12:13]
	global_load_dword v212, v[198:199], off
	v_or_b32_e32 v200, s84, v1
	v_ashrrev_i32_e32 v201, 31, v200
	v_lshl_add_u64 v[200:201], v[200:201], 2, s[12:13]
	global_load_dword v213, v[200:201], off
	v_or_b32_e32 v202, s84, v184
	v_ashrrev_i32_e32 v203, 31, v202
	v_lshl_add_u64 v[202:203], v[202:203], 2, s[12:13]
	global_load_dword v214, v[202:203], off
	v_or_b32_e32 v204, s84, v185
	v_ashrrev_i32_e32 v205, 31, v204
	v_lshl_add_u64 v[204:205], v[204:205], 2, s[12:13]
	global_load_dword v215, v[204:205], off
	v_or_b32_e32 v206, s84, v186
	v_ashrrev_i32_e32 v207, 31, v206
	v_lshl_add_u64 v[206:207], v[206:207], 2, s[12:13]
	global_load_dword v216, v[206:207], off
	v_readlane_b32 s36, v254, 2
	s_cmp_gt_i32 s4, 3
	v_readlane_b32 s37, v254, 3
	s_mov_b32 s36, s30
	s_cselect_b64 s[34:35], -1, 0
	s_cmp_gt_u32 s4, 5
	v_writelane_b32 v254, s36, 2
	s_cselect_b64 s[28:29], -1, 0
	s_bfe_u32 s23, s21, 0x60006
	v_writelane_b32 v254, s37, 3
	s_mov_b64 s[36:37], -1
	s_and_b64 vcc, exec, s[34:35]
	s_waitcnt vmcnt(0)
	v_fmamk_f32 v166, v166, 0x3a800000, v225
	v_rsq_f32_e32 v174, v166
	s_nop 0
	v_pk_fma_f32 v[166:167], v[144:145], v[174:175], v[64:65] op_sel_hi:[1,0,1]
	v_pk_fma_f32 v[144:145], v[130:131], v[174:175], v[50:51] op_sel_hi:[1,0,1]
	v_cndmask_b32_e64 v130, 0, 1, s[0:1]
	v_pk_fma_f32 v[168:169], v[142:143], v[174:175], v[62:63] op_sel_hi:[1,0,1]
	v_pk_fma_f32 v[140:141], v[140:141], v[174:175], v[60:61] op_sel_hi:[1,0,1]
	v_pk_fma_f32 v[138:139], v[138:139], v[174:175], v[58:59] op_sel_hi:[1,0,1]
	v_pk_fma_f32 v[170:171], v[136:137], v[174:175], v[56:57] op_sel_hi:[1,0,1]
	v_pk_fma_f32 v[172:173], v[134:135], v[174:175], v[54:55] op_sel_hi:[1,0,1]
	v_pk_fma_f32 v[142:143], v[132:133], v[174:175], v[52:53] op_sel_hi:[1,0,1]
	v_cmp_ne_u32_e64 s[0:1], 1, v130
	s_cbranch_vccz .LBB0_890
	s_and_b64 vcc, exec, s[0:1]
	s_cbranch_vccnz .LBB0_884
	v_mov_b32_e32 v130, s23
	v_cndmask_b32_e64 v130, v1, v130, s[6:7]
	v_lshlrev_b32_e32 v130, 6, v130
	v_mov_b32_e32 v131, v0
	v_lshl_add_u64 v[132:133], v[154:155], 0, v[130:131]
	v_lshl_add_u64 v[130:131], v[156:157], 0, v[130:131]
	global_load_dwordx4 v[134:137], v[130:131], off
	s_nop 0
	global_load_dwordx4 v[130:133], v[132:133], off
	s_branch .LBB0_885

.LBB0_892:
	v_or_b32_e32 v132, s21, v184
	v_cvt_pk_bf16_f32 v179, v176, v177
	v_ashrrev_i32_e32 v133, 31, v132
	global_store_dwordx2 v[174:175], v[178:179], off offset:32
	v_lshl_add_u64 v[134:135], v[132:133], 2, s[12:13]
	s_nop 0
	v_readlane_b32 s54, v254, 16
	s_andn2_b64 vcc, exec, s[34:35]
	v_readlane_b32 s55, v254, 17
	s_movk_i32 s56, 0x3fff
	v_fmamk_f32 v131, v210, 0x3a800000, v225
	v_rsq_f32_e32 v142, v131
	v_cndmask_b32_e64 v131, 0, 1, s[34:35]
	v_cmp_ne_u32_e64 s[4:5], 1, v131
	s_mov_b64 s[34:35], -1
	v_pk_fma_f32 v[134:135], v[128:129], v[142:143], v[64:65] op_sel_hi:[1,0,1]
	v_pk_fma_f32 v[136:137], v[126:127], v[142:143], v[62:63] op_sel_hi:[1,0,1]
	v_pk_fma_f32 v[124:125], v[124:125], v[142:143], v[60:61] op_sel_hi:[1,0,1]
	v_pk_fma_f32 v[122:123], v[122:123], v[142:143], v[58:59] op_sel_hi:[1,0,1]
	v_pk_fma_f32 v[138:139], v[120:121], v[142:143], v[56:57] op_sel_hi:[1,0,1]
	v_pk_fma_f32 v[140:141], v[118:119], v[142:143], v[54:55] op_sel_hi:[1,0,1]
	v_pk_fma_f32 v[126:127], v[116:117], v[142:143], v[52:53] op_sel_hi:[1,0,1]
	v_pk_fma_f32 v[128:129], v[114:115], v[142:143], v[50:51] op_sel_hi:[1,0,1]
	s_cbranch_vccnz .LBB0_900
	s_and_b64 vcc, exec, s[0:1]
	s_cbranch_vccnz .LBB0_895
	v_mov_b32_e32 v114, s23
	v_cndmask_b32_e64 v114, v184, v114, s[6:7]
	v_lshlrev_b32_e32 v114, 6, v114
	v_mov_b32_e32 v115, v0
	v_lshl_add_u64 v[116:117], v[154:155], 0, v[114:115]
	v_lshl_add_u64 v[114:115], v[156:157], 0, v[114:115]
	global_load_dwordx4 v[118:121], v[114:115], off
	s_nop 0
	global_load_dwordx4 v[114:117], v[116:117], off
	s_andn2_b64 vcc, exec, s[28:29]
	s_waitcnt vmcnt(0)
	v_pk_mul_f32 v[168:169], v[122:123], v[114:115]
	v_pk_mul_f32 v[166:167], v[122:123], v[118:119]
	s_cbranch_vccnz .LBB0_897
	s_branch .LBB0_896

.LBB0_902:
	v_or_b32_e32 v114, s21, v185
	v_cvt_pk_bf16_f32 v165, v144, v145
	v_ashrrev_i32_e32 v115, 31, v114
	global_store_dwordx2 v[142:143], v[164:165], off offset:32
	v_lshl_add_u64 v[116:117], v[114:115], 2, s[12:13]
	s_nop 0
	s_and_b64 vcc, exec, s[4:5]
	s_mov_b64 s[34:35], -1
	v_fmamk_f32 v116, v211, 0x3a800000, v225
	v_rsq_f32_e32 v124, v116
	s_nop 0
	v_pk_fma_f32 v[116:117], v[112:113], v[124:125], v[64:65] op_sel_hi:[1,0,1]
	v_pk_fma_f32 v[118:119], v[110:111], v[124:125], v[62:63] op_sel_hi:[1,0,1]
	v_pk_fma_f32 v[108:109], v[108:109], v[124:125], v[60:61] op_sel_hi:[1,0,1]
	v_pk_fma_f32 v[106:107], v[106:107], v[124:125], v[58:59] op_sel_hi:[1,0,1]
	v_pk_fma_f32 v[120:121], v[104:105], v[124:125], v[56:57] op_sel_hi:[1,0,1]
	v_pk_fma_f32 v[122:123], v[102:103], v[124:125], v[54:55] op_sel_hi:[1,0,1]
	v_pk_fma_f32 v[110:111], v[100:101], v[124:125], v[52:53] op_sel_hi:[1,0,1]
	v_pk_fma_f32 v[112:113], v[98:99], v[124:125], v[50:51] op_sel_hi:[1,0,1]
	s_cbranch_vccnz .LBB0_910
	s_and_b64 vcc, exec, s[0:1]
	s_cbranch_vccnz .LBB0_905
	v_mov_b32_e32 v98, s23
	v_cndmask_b32_e64 v98, v185, v98, s[6:7]
	v_lshlrev_b32_e32 v98, 6, v98
	v_mov_b32_e32 v99, v0
	v_lshl_add_u64 v[100:101], v[154:155], 0, v[98:99]
	v_lshl_add_u64 v[98:99], v[156:157], 0, v[98:99]
	global_load_dwordx4 v[102:105], v[98:99], off
	s_nop 0
	global_load_dwordx4 v[98:101], v[100:101], off
	s_andn2_b64 vcc, exec, s[28:29]
	s_waitcnt vmcnt(0)
	v_pk_mul_f32 v[134:135], v[106:107], v[98:99]
	v_pk_mul_f32 v[132:133], v[106:107], v[102:103]
	s_cbranch_vccnz .LBB0_907
	s_branch .LBB0_906

.LBB0_912:
	v_or_b32_e32 v98, s21, v186
	v_cvt_pk_bf16_f32 v129, v126, v127
	v_ashrrev_i32_e32 v99, 31, v98
	global_store_dwordx2 v[124:125], v[128:129], off offset:32
	v_lshl_add_u64 v[100:101], v[98:99], 2, s[12:13]
	s_nop 0
	s_and_b64 vcc, exec, s[4:5]
	s_mov_b64 s[34:35], -1
	v_fmamk_f32 v100, v212, 0x3a800000, v225
	v_rsq_f32_e32 v108, v100
	s_nop 0
	v_pk_fma_f32 v[100:101], v[96:97], v[108:109], v[64:65] op_sel_hi:[1,0,1]
	v_pk_fma_f32 v[102:103], v[94:95], v[108:109], v[62:63] op_sel_hi:[1,0,1]
	v_pk_fma_f32 v[92:93], v[92:93], v[108:109], v[60:61] op_sel_hi:[1,0,1]
	v_pk_fma_f32 v[90:91], v[90:91], v[108:109], v[58:59] op_sel_hi:[1,0,1]
	v_pk_fma_f32 v[104:105], v[88:89], v[108:109], v[56:57] op_sel_hi:[1,0,1]
	v_pk_fma_f32 v[106:107], v[86:87], v[108:109], v[54:55] op_sel_hi:[1,0,1]
	v_pk_fma_f32 v[94:95], v[84:85], v[108:109], v[52:53] op_sel_hi:[1,0,1]
	v_pk_fma_f32 v[96:97], v[82:83], v[108:109], v[50:51] op_sel_hi:[1,0,1]
	s_cbranch_vccnz .LBB0_920
	s_and_b64 vcc, exec, s[0:1]
	s_cbranch_vccnz .LBB0_915
	v_mov_b32_e32 v82, s23
	v_cndmask_b32_e64 v82, v186, v82, s[6:7]
	v_lshlrev_b32_e32 v82, 6, v82
	v_mov_b32_e32 v83, v0
	v_lshl_add_u64 v[84:85], v[154:155], 0, v[82:83]
	v_lshl_add_u64 v[82:83], v[156:157], 0, v[82:83]
	global_load_dwordx4 v[86:89], v[82:83], off
	s_nop 0
	global_load_dwordx4 v[82:85], v[84:85], off
	s_andn2_b64 vcc, exec, s[28:29]
	s_waitcnt vmcnt(0)
	v_pk_mul_f32 v[116:117], v[90:91], v[82:83]
	v_pk_mul_f32 v[114:115], v[90:91], v[86:87]
	s_cbranch_vccnz .LBB0_917
	s_branch .LBB0_916

.LBB0_922:
	s_add_i32 s23, s21, 0x80
	v_or_b32_e32 v82, s23, v1
	v_cvt_pk_bf16_f32 v113, v110, v111
	v_ashrrev_i32_e32 v83, 31, v82
	global_store_dwordx2 v[108:109], v[112:113], off offset:32
	v_lshl_add_u64 v[84:85], v[82:83], 2, s[12:13]
	s_nop 0
	s_and_b64 vcc, exec, s[4:5]
	s_bfe_u32 s21, s23, 0x60006
	s_mov_b64 s[34:35], -1
	v_fmamk_f32 v84, v213, 0x3a800000, v225
	v_rsq_f32_e32 v92, v84
	s_nop 0
	v_pk_fma_f32 v[84:85], v[80:81], v[92:93], v[64:65] op_sel_hi:[1,0,1]
	v_pk_fma_f32 v[86:87], v[78:79], v[92:93], v[62:63] op_sel_hi:[1,0,1]
	v_pk_fma_f32 v[76:77], v[76:77], v[92:93], v[60:61] op_sel_hi:[1,0,1]
	v_pk_fma_f32 v[74:75], v[74:75], v[92:93], v[58:59] op_sel_hi:[1,0,1]
	v_pk_fma_f32 v[88:89], v[72:73], v[92:93], v[56:57] op_sel_hi:[1,0,1]
	v_pk_fma_f32 v[90:91], v[70:71], v[92:93], v[54:55] op_sel_hi:[1,0,1]
	v_pk_fma_f32 v[78:79], v[68:69], v[92:93], v[52:53] op_sel_hi:[1,0,1]
	v_pk_fma_f32 v[80:81], v[66:67], v[92:93], v[50:51] op_sel_hi:[1,0,1]
	s_cbranch_vccnz .LBB0_930
	s_and_b64 vcc, exec, s[0:1]
	s_cbranch_vccnz .LBB0_925
	v_mov_b32_e32 v66, s21
	v_cndmask_b32_e64 v66, v1, v66, s[6:7]
	v_lshlrev_b32_e32 v66, 6, v66
	v_mov_b32_e32 v67, v0
	v_lshl_add_u64 v[68:69], v[154:155], 0, v[66:67]
	v_lshl_add_u64 v[66:67], v[156:157], 0, v[66:67]
	global_load_dwordx4 v[70:73], v[66:67], off
	s_nop 0
	global_load_dwordx4 v[66:69], v[68:69], off
	s_andn2_b64 vcc, exec, s[28:29]
	s_waitcnt vmcnt(0)
	v_pk_mul_f32 v[100:101], v[74:75], v[66:67]
	v_pk_mul_f32 v[98:99], v[74:75], v[70:71]
	s_cbranch_vccnz .LBB0_927
	s_branch .LBB0_926

.LBB0_932:
	v_or_b32_e32 v66, s23, v184
	v_cvt_pk_bf16_f32 v97, v94, v95
	v_ashrrev_i32_e32 v67, 31, v66
	global_store_dwordx2 v[92:93], v[96:97], off offset:32
	v_lshl_add_u64 v[68:69], v[66:67], 2, s[12:13]
	s_nop 0
	s_and_b64 vcc, exec, s[4:5]
	s_mov_b64 s[34:35], -1
	v_fmamk_f32 v68, v214, 0x3a800000, v225
	v_rsq_f32_e32 v76, v68
	s_nop 0
	v_pk_fma_f32 v[68:69], v[48:49], v[76:77], v[64:65] op_sel_hi:[1,0,1]
	v_pk_fma_f32 v[70:71], v[46:47], v[76:77], v[62:63] op_sel_hi:[1,0,1]
	v_pk_fma_f32 v[44:45], v[44:45], v[76:77], v[60:61] op_sel_hi:[1,0,1]
	v_pk_fma_f32 v[42:43], v[42:43], v[76:77], v[58:59] op_sel_hi:[1,0,1]
	v_pk_fma_f32 v[72:73], v[40:41], v[76:77], v[56:57] op_sel_hi:[1,0,1]
	v_pk_fma_f32 v[74:75], v[38:39], v[76:77], v[54:55] op_sel_hi:[1,0,1]
	v_pk_fma_f32 v[46:47], v[36:37], v[76:77], v[52:53] op_sel_hi:[1,0,1]
	v_pk_fma_f32 v[48:49], v[34:35], v[76:77], v[50:51] op_sel_hi:[1,0,1]
	s_cbranch_vccnz .LBB0_940
	s_and_b64 vcc, exec, s[0:1]
	s_cbranch_vccnz .LBB0_935
	v_mov_b32_e32 v34, s21
	v_cndmask_b32_e64 v34, v184, v34, s[6:7]
	v_lshlrev_b32_e32 v34, 6, v34
	v_mov_b32_e32 v35, v0
	v_lshl_add_u64 v[36:37], v[154:155], 0, v[34:35]
	v_lshl_add_u64 v[34:35], v[156:157], 0, v[34:35]
	global_load_dwordx4 v[38:41], v[34:35], off
	s_nop 0
	global_load_dwordx4 v[34:37], v[36:37], off
	s_andn2_b64 vcc, exec, s[28:29]
	s_waitcnt vmcnt(0)
	v_pk_mul_f32 v[84:85], v[42:43], v[34:35]
	v_pk_mul_f32 v[82:83], v[42:43], v[38:39]
	s_cbranch_vccnz .LBB0_937
	s_branch .LBB0_936

.LBB0_942:
	v_or_b32_e32 v34, s23, v185
	v_cvt_pk_bf16_f32 v81, v78, v79
	v_ashrrev_i32_e32 v35, 31, v34
	global_store_dwordx2 v[76:77], v[80:81], off offset:32
	v_lshl_add_u64 v[36:37], v[34:35], 2, s[12:13]
	s_nop 0
	s_and_b64 vcc, exec, s[4:5]
	s_mov_b64 s[34:35], -1
	v_fmamk_f32 v36, v215, 0x3a800000, v225
	v_rsq_f32_e32 v44, v36
	s_nop 0
	v_pk_fma_f32 v[36:37], v[32:33], v[44:45], v[64:65] op_sel_hi:[1,0,1]
	v_pk_fma_f32 v[38:39], v[30:31], v[44:45], v[62:63] op_sel_hi:[1,0,1]
	v_pk_fma_f32 v[28:29], v[28:29], v[44:45], v[60:61] op_sel_hi:[1,0,1]
	v_pk_fma_f32 v[26:27], v[26:27], v[44:45], v[58:59] op_sel_hi:[1,0,1]
	v_pk_fma_f32 v[40:41], v[24:25], v[44:45], v[56:57] op_sel_hi:[1,0,1]
	v_pk_fma_f32 v[42:43], v[22:23], v[44:45], v[54:55] op_sel_hi:[1,0,1]
	v_pk_fma_f32 v[30:31], v[20:21], v[44:45], v[52:53] op_sel_hi:[1,0,1]
	v_pk_fma_f32 v[32:33], v[18:19], v[44:45], v[50:51] op_sel_hi:[1,0,1]
	s_cbranch_vccnz .LBB0_950
	s_and_b64 vcc, exec, s[0:1]
	s_cbranch_vccnz .LBB0_945
	v_mov_b32_e32 v18, s21
	v_cndmask_b32_e64 v18, v185, v18, s[6:7]
	v_lshlrev_b32_e32 v18, 6, v18
	v_mov_b32_e32 v19, v0
	v_lshl_add_u64 v[20:21], v[154:155], 0, v[18:19]
	v_lshl_add_u64 v[18:19], v[156:157], 0, v[18:19]
	global_load_dwordx4 v[22:25], v[18:19], off
	s_nop 0
	global_load_dwordx4 v[18:21], v[20:21], off
	s_andn2_b64 vcc, exec, s[28:29]
	s_waitcnt vmcnt(0)
	v_pk_mul_f32 v[68:69], v[26:27], v[18:19]
	v_pk_mul_f32 v[66:67], v[26:27], v[22:23]
	s_cbranch_vccnz .LBB0_947
	s_branch .LBB0_946

.LBB0_952:
	v_or_b32_e32 v18, s23, v186
	v_cvt_pk_bf16_f32 v49, v46, v47
	v_ashrrev_i32_e32 v19, 31, v18
	global_store_dwordx2 v[44:45], v[48:49], off offset:32
	v_lshl_add_u64 v[20:21], v[18:19], 2, s[12:13]
	s_nop 0
	s_and_b64 vcc, exec, s[4:5]
	s_mov_b64 s[4:5], -1
	v_fmamk_f32 v20, v216, 0x3a800000, v225
	v_rsq_f32_e32 v28, v20
	s_nop 0
	v_pk_fma_f32 v[20:21], v[16:17], v[28:29], v[64:65] op_sel_hi:[1,0,1]
	v_pk_fma_f32 v[22:23], v[14:15], v[28:29], v[62:63] op_sel_hi:[1,0,1]
	v_pk_fma_f32 v[12:13], v[12:13], v[28:29], v[60:61] op_sel_hi:[1,0,1]
	v_pk_fma_f32 v[10:11], v[10:11], v[28:29], v[58:59] op_sel_hi:[1,0,1]
	v_pk_fma_f32 v[24:25], v[8:9], v[28:29], v[56:57] op_sel_hi:[1,0,1]
	v_pk_fma_f32 v[26:27], v[6:7], v[28:29], v[54:55] op_sel_hi:[1,0,1]
	v_pk_fma_f32 v[14:15], v[4:5], v[28:29], v[52:53] op_sel_hi:[1,0,1]
	v_pk_fma_f32 v[16:17], v[2:3], v[28:29], v[50:51] op_sel_hi:[1,0,1]
	s_cbranch_vccnz .LBB0_961
	s_and_b64 vcc, exec, s[0:1]
	s_cbranch_vccnz .LBB0_955
	v_mov_b32_e32 v2, s21
	v_cndmask_b32_e64 v2, v186, v2, s[6:7]
	v_lshlrev_b32_e32 v2, 6, v2
	v_mov_b32_e32 v3, v0
	v_lshl_add_u64 v[4:5], v[154:155], 0, v[2:3]
	v_lshl_add_u64 v[2:3], v[156:157], 0, v[2:3]
	global_load_dwordx4 v[6:9], v[2:3], off
	s_nop 0
	global_load_dwordx4 v[2:5], v[4:5], off
	s_branch .LBB0_956
